# FoX: each wave takes two adjacent query tiles of one head so every K/V fragment load feeds both tiles; waves w and w+4 take mirrored pairs
# speedup vs baseline: 1.0132x; 1.0132x over previous
.Lfox_entry:
	s_waitcnt vmcnt(0)
	v_lshlrev_b32_e32 v2, 2, v220
	v_add_u32_e32 v3, 0x10000, v2
	ds_write_b32 v2, v146 offset:0
	ds_write_b32 v2, v147 offset:2048
	ds_write_b32 v2, v148 offset:4096
	ds_write_b32 v2, v149 offset:6144
	ds_write_b32 v2, v150 offset:8192
	ds_write_b32 v2, v151 offset:10240
	ds_write_b32 v2, v152 offset:12288
	ds_write_b32 v2, v153 offset:14336
	ds_write_b32 v2, v154 offset:16384
	ds_write_b32 v2, v155 offset:18432
	ds_write_b32 v2, v156 offset:20480
	ds_write_b32 v2, v157 offset:22528
	ds_write_b32 v2, v158 offset:24576
	ds_write_b32 v2, v159 offset:26624
	ds_write_b32 v2, v160 offset:28672
	ds_write_b32 v2, v161 offset:30720
	ds_write_b32 v2, v162 offset:32768
	ds_write_b32 v2, v163 offset:34816
	ds_write_b32 v2, v164 offset:36864
	ds_write_b32 v2, v165 offset:38912
	ds_write_b32 v2, v166 offset:40960
	ds_write_b32 v2, v167 offset:43008
	ds_write_b32 v2, v168 offset:45056
	ds_write_b32 v2, v169 offset:47104
	ds_write_b32 v2, v170 offset:49152
	ds_write_b32 v2, v183 offset:51200
	ds_write_b32 v2, v184 offset:53248
	ds_write_b32 v2, v185 offset:55296
	ds_write_b32 v2, v186 offset:57344
	ds_write_b32 v2, v187 offset:59392
	ds_write_b32 v2, v188 offset:61440
	ds_write_b32 v2, v189 offset:63488
	ds_write_b32 v3, v190 offset:0
	ds_write_b32 v3, v191 offset:2048
	ds_write_b32 v3, v192 offset:4096
	ds_write_b32 v3, v193 offset:6144
	ds_write_b32 v3, v194 offset:8192
	ds_write_b32 v3, v195 offset:10240
	ds_write_b32 v3, v196 offset:12288
	ds_write_b32 v3, v197 offset:14336
	ds_write_b32 v3, v198 offset:16384
	ds_write_b32 v3, v199 offset:18432
	ds_write_b32 v3, v200 offset:20480
	ds_write_b32 v3, v201 offset:22528
	ds_write_b32 v3, v202 offset:24576
	ds_write_b32 v3, v203 offset:26624
	ds_write_b32 v3, v204 offset:28672
	ds_write_b32 v3, v205 offset:30720
	ds_write_b32 v3, v206 offset:32768
	ds_write_b32 v3, v207 offset:34816
	ds_write_b32 v3, v208 offset:36864
	ds_write_b32 v3, v209 offset:38912
	ds_write_b32 v3, v210 offset:40960
	ds_write_b32 v3, v211 offset:43008
	ds_write_b32 v3, v212 offset:45056
	ds_write_b32 v3, v213 offset:47104
	ds_write_b32 v3, v214 offset:49152
	ds_write_b32 v3, v215 offset:51200
	ds_write_b32 v3, v216 offset:53248
	v_lshrrev_b32_e32 v2, 6, v220
	v_lshlrev_b32_e32 v2, 8, v2
	v_add_u32_e32 v2, 0x1d800, v2
	v_mov_b32_e32 v3, s2
	ds_write_b32 v2, v3 offset:0
	v_mov_b32_e32 v3, s3
	ds_write_b32 v2, v3 offset:4
	v_mov_b32_e32 v3, s4
	ds_write_b32 v2, v3 offset:8
	v_mov_b32_e32 v3, s5
	ds_write_b32 v2, v3 offset:12
	v_mov_b32_e32 v3, s6
	ds_write_b32 v2, v3 offset:16
	v_mov_b32_e32 v3, s7
	ds_write_b32 v2, v3 offset:20
	v_mov_b32_e32 v3, s8
	ds_write_b32 v2, v3 offset:24
	v_mov_b32_e32 v3, s9
	ds_write_b32 v2, v3 offset:28
	v_mov_b32_e32 v3, s10
	ds_write_b32 v2, v3 offset:32
	v_mov_b32_e32 v3, s11
	ds_write_b32 v2, v3 offset:36
	v_mov_b32_e32 v3, s12
	ds_write_b32 v2, v3 offset:40
	v_mov_b32_e32 v3, s13
	ds_write_b32 v2, v3 offset:44
	v_mov_b32_e32 v3, s14
	ds_write_b32 v2, v3 offset:48
	v_mov_b32_e32 v3, s15
	ds_write_b32 v2, v3 offset:52
	v_mov_b32_e32 v3, s16
	ds_write_b32 v2, v3 offset:56
	v_mov_b32_e32 v3, s17
	ds_write_b32 v2, v3 offset:60
	v_mov_b32_e32 v3, s18
	ds_write_b32 v2, v3 offset:64
	v_mov_b32_e32 v3, s19
	ds_write_b32 v2, v3 offset:68
	v_mov_b32_e32 v3, s20
	ds_write_b32 v2, v3 offset:72
	v_mov_b32_e32 v3, s21
	ds_write_b32 v2, v3 offset:76
	v_mov_b32_e32 v3, s22
	ds_write_b32 v2, v3 offset:80
	v_mov_b32_e32 v3, s23
	ds_write_b32 v2, v3 offset:84
	v_mov_b32_e32 v3, s24
	ds_write_b32 v2, v3 offset:88
	v_mov_b32_e32 v3, s25
	ds_write_b32 v2, v3 offset:92
	v_mov_b32_e32 v3, s26
	ds_write_b32 v2, v3 offset:96
	v_mov_b32_e32 v3, s27
	ds_write_b32 v2, v3 offset:100
	v_mov_b32_e32 v3, s28
	ds_write_b32 v2, v3 offset:104
	v_mov_b32_e32 v3, s29
	ds_write_b32 v2, v3 offset:108
	v_mov_b32_e32 v3, s30
	ds_write_b32 v2, v3 offset:112
	v_mov_b32_e32 v3, s31
	ds_write_b32 v2, v3 offset:116
	v_mov_b32_e32 v3, s34
	ds_write_b32 v2, v3 offset:120
	v_mov_b32_e32 v3, s35
	ds_write_b32 v2, v3 offset:124
	v_mov_b32_e32 v3, s36
	ds_write_b32 v2, v3 offset:128
	v_mov_b32_e32 v3, s37
	ds_write_b32 v2, v3 offset:132
	v_mov_b32_e32 v3, s38
	ds_write_b32 v2, v3 offset:136
	v_mov_b32_e32 v3, s39
	ds_write_b32 v2, v3 offset:140
	v_mov_b32_e32 v3, s40
	ds_write_b32 v2, v3 offset:144
	v_mov_b32_e32 v3, s41
	ds_write_b32 v2, v3 offset:148
	v_mov_b32_e32 v3, s42
	ds_write_b32 v2, v3 offset:152
	v_mov_b32_e32 v3, s43
	ds_write_b32 v2, v3 offset:156
	v_mov_b32_e32 v3, s44
	ds_write_b32 v2, v3 offset:160
	v_mov_b32_e32 v3, s45
	ds_write_b32 v2, v3 offset:164
	s_load_dwordx2 s[20:21], s[70:71], 0x98
	v_readlane_b32 s22, v254, 0
	v_and_b32_e32 v195, 31, v173
	v_lshrrev_b32_e32 v196, 5, v173
	v_lshlrev_b32_e32 v194, 4, v173
	v_lshlrev_b32_e32 v190, 4, v195
	v_mov_b32_e32 v193, 0xff800000
	v_lshlrev_b32_e32 v183, 2, v196
	v_sub_u32_e32 v170, v195, v183
	v_xor_b32_e32 v192, 32, v173
	v_lshlrev_b32_e32 v192, 2, v192
	s_mov_b32 s14, 0x3e38aa3b
	s_mov_b32 s44, -1
	s_mov_b32 s45, 0
	v_cmp_eq_u32_e32 vcc, 0, v196
	v_mov_b32_e32 v183, 0x3f803f80
	v_mov_b32_e32 v184, 0x3f80
	s_nop 0
	v_cndmask_b32_e32 v70, 0, v183, vcc
	v_cndmask_b32_e32 v71, 0, v184, vcc
	v_mov_b32_e32 v72, 0
	v_mov_b32_e32 v73, 0
	v_mov_b32_e32 v18, 0
	v_mov_b32_e32 v19, 0
	v_mov_b32_e32 v20, 0
	v_mov_b32_e32 v21, 0
	s_waitcnt lgkmcnt(0)
.Lfox_outer:
	s_lshr_b32 s23, s22, 6
	s_and_b32 s24, s22, 63
	s_sub_i32 s17, 0x43, s24
	s_bitcmp1_b32 s22, 2
	s_cselect_b32 s24, s17, s24
	s_lshl_b32 s15, s24, 1
	s_lshr_b32 s25, s23, 2
	s_and_b32 s26, s23, 3
	s_lshl_b32 s17, s23, 19
	s_add_u32 s4, s20, s17
	s_addc_u32 s5, s21, 0
	s_add_u32 s6, s4, 0x1c600000
	s_addc_u32 s7, s5, 0
	s_add_u32 s4, s4, 0x1b600000
	s_addc_u32 s5, s5, 0
	s_lshl_b32 s17, s23, 16
	s_add_u32 s8, s20, s17
	s_addc_u32 s9, s21, 0
	s_add_u32 s8, s8, 0x2880000
	s_addc_u32 s9, s9, 0
	s_lshl_b32 s17, s23, 14
	s_add_u32 s10, s20, s17
	s_addc_u32 s11, s21, 0
	s_add_u32 s10, s10, 0x1da00000
	s_addc_u32 s11, s11, 0
	s_lshl_b32 s17, s25, 23
	s_lshl_b32 s18, s26, 7
	s_add_i32 s17, s17, s18
	s_add_u32 s12, s20, s17
	s_addc_u32 s13, s21, 0
	s_add_u32 s12, s12, 0x14600000
	s_addc_u32 s13, s13, 0
	s_add_u32 s2, s20, 0x5600000
	s_addc_u32 s3, s21, 0
	s_lshl_b32 s27, s25, 12
	v_lshl_add_u32 v183, s15, 5, v195
	v_lshlrev_b32_e32 v205, 11, v183
	v_lshl_add_u32 v205, v196, 3, v205
	v_add_u32_e32 v206, 0x10000, v205
	v_lshlrev_b32_e32 v184, 2, v183
	global_load_dword v199, v184, s[10:11]
	global_load_dword v203, v184, s[10:11] offset:128
	v_add_u32_e32 v183, s27, v183
	v_mul_u32_u24_e32 v183, 0x1600, v183
	v_lshl_add_u32 v183, v196, 4, v183
	s_lshl_b32 s17, s26, 7
	v_add_u32_e32 v183, s17, v183
	v_add_u32_e32 v184, 0x2c000, v183
	global_load_dwordx4 v[38:41], v183, s[2:3]
	global_load_dwordx4 v[42:45], v183, s[2:3] offset:32
	global_load_dwordx4 v[46:49], v183, s[2:3] offset:64
	global_load_dwordx4 v[50:53], v183, s[2:3] offset:96
	global_load_dwordx4 v[54:57], v184, s[2:3]
	global_load_dwordx4 v[58:61], v184, s[2:3] offset:32
	global_load_dwordx4 v[62:65], v184, s[2:3] offset:64
	global_load_dwordx4 v[66:69], v184, s[2:3] offset:96
	s_mov_b32 s16, 0
	s_lshl_b32 s17, s16, 12
	v_add_u32_e32 v207, s17, v194
	global_load_dwordx4 v[2:5], v207, s[4:5]
	global_load_dwordx4 v[6:9], v207, s[4:5] offset:1024
	global_load_dwordx4 v[10:13], v207, s[4:5] offset:2048
	global_load_dwordx4 v[14:17], v207, s[4:5] offset:3072
	s_lshl_b32 s17, s16, 9
	v_add_u32_e32 v209, s17, v190
	s_mov_b64 exec, s[44:45]
	global_load_dwordx4 v[18:21], v209, s[8:9]
	s_mov_b64 exec, -1
	s_lshl_b32 s17, s16, 12
	v_add_u32_e32 v208, s17, v194
	global_load_dwordx4 v[22:25], v208, s[6:7]
	global_load_dwordx4 v[26:29], v208, s[6:7] offset:1024
	global_load_dwordx4 v[30:33], v208, s[6:7] offset:2048
	global_load_dwordx4 v[34:37], v208, s[6:7] offset:3072
	v_mov_b32_e32 v197, 0xf149f2ca
	v_mov_b32_e32 v198, 0
	v_mov_b32_e32 v74, 0
	v_mov_b32_e32 v75, 0
	v_mov_b32_e32 v76, 0
	v_mov_b32_e32 v77, 0
	v_mov_b32_e32 v78, 0
	v_mov_b32_e32 v79, 0
	v_mov_b32_e32 v80, 0
	v_mov_b32_e32 v81, 0
	v_mov_b32_e32 v82, 0
	v_mov_b32_e32 v83, 0
	v_mov_b32_e32 v84, 0
	v_mov_b32_e32 v85, 0
	v_mov_b32_e32 v86, 0
	v_mov_b32_e32 v87, 0
	v_mov_b32_e32 v88, 0
	v_mov_b32_e32 v89, 0
	v_mov_b32_e32 v90, 0
	v_mov_b32_e32 v91, 0
	v_mov_b32_e32 v92, 0
	v_mov_b32_e32 v93, 0
	v_mov_b32_e32 v94, 0
	v_mov_b32_e32 v95, 0
	v_mov_b32_e32 v96, 0
	v_mov_b32_e32 v97, 0
	v_mov_b32_e32 v98, 0
	v_mov_b32_e32 v99, 0
	v_mov_b32_e32 v100, 0
	v_mov_b32_e32 v101, 0
	v_mov_b32_e32 v102, 0
	v_mov_b32_e32 v103, 0
	v_mov_b32_e32 v104, 0
	v_mov_b32_e32 v105, 0
	v_mov_b32_e32 v201, 0xf149f2ca
	v_mov_b32_e32 v202, 0
	v_mov_b32_e32 v106, 0
	v_mov_b32_e32 v107, 0
	v_mov_b32_e32 v108, 0
	v_mov_b32_e32 v109, 0
	v_mov_b32_e32 v110, 0
	v_mov_b32_e32 v111, 0
	v_mov_b32_e32 v112, 0
	v_mov_b32_e32 v113, 0
	v_mov_b32_e32 v114, 0
	v_mov_b32_e32 v115, 0
	v_mov_b32_e32 v116, 0
	v_mov_b32_e32 v117, 0
	v_mov_b32_e32 v118, 0
	v_mov_b32_e32 v119, 0
	v_mov_b32_e32 v120, 0
	v_mov_b32_e32 v121, 0
	v_mov_b32_e32 v122, 0
	v_mov_b32_e32 v123, 0
	v_mov_b32_e32 v124, 0
	v_mov_b32_e32 v125, 0
	v_mov_b32_e32 v126, 0
	v_mov_b32_e32 v127, 0
	v_mov_b32_e32 v128, 0
	v_mov_b32_e32 v129, 0
	v_mov_b32_e32 v130, 0
	v_mov_b32_e32 v131, 0
	v_mov_b32_e32 v132, 0
	v_mov_b32_e32 v133, 0
	v_mov_b32_e32 v134, 0
	v_mov_b32_e32 v135, 0
	v_mov_b32_e32 v136, 0
	v_mov_b32_e32 v137, 0
	s_waitcnt vmcnt(9)
	v_mul_f32_e32 v199, 0x3fb8aa3b, v199
	v_mul_f32_e32 v203, 0x3fb8aa3b, v203
	s_cmp_eq_u32 s15, 0
	s_cbranch_scc1 .Lfox_tail
.Lfox_loop:
	s_waitcnt vmcnt(4)
	v_mfma_f32_32x32x16_bf16 v[138:153], v[2:5], v[38:41], 0
	v_mfma_f32_32x32x16_bf16 v[138:153], v[6:9], v[42:45], v[138:153]
	v_mfma_f32_32x32x16_bf16 v[138:153], v[10:13], v[46:49], v[138:153]
	v_mfma_f32_32x32x16_bf16 v[138:153], v[14:17], v[50:53], v[138:153]
	v_mfma_f32_32x32x16_bf16 v[138:153], v[18:21], v[70:73], v[138:153]
	v_mfma_f32_32x32x16_bf16 v[154:169], v[2:5], v[54:57], 0
	s_nop 7
	s_nop 4
	v_max3_f32 v183, v138, v139, v140
	v_max3_f32 v184, v141, v142, v143
	v_max3_f32 v185, v144, v145, v146
	v_max3_f32 v186, v147, v148, v149
	v_max3_f32 v187, v150, v151, v152
	v_max3_f32 v183, v183, v184, v185
	v_max3_f32 v186, v186, v187, v153
	v_max_f32_e32 v183, v183, v186
	ds_bpermute_b32 v184, v192, v183
	s_waitcnt lgkmcnt(0)
	v_max_f32_e32 v183, v183, v184
	v_fma_f32 v183, v183, s14, v199
	v_max_f32_e32 v184, v197, v183
	v_sub_f32_e32 v186, v197, v184
	v_mfma_f32_32x32x16_bf16 v[154:169], v[6:9], v[58:61], v[154:169]
	v_exp_f32_e32 v186, v186
	v_mov_b32_e32 v197, v184
	v_sub_f32_e32 v200, v199, v184
	v_fma_f32 v138, v138, s14, v200
	v_exp_f32_e32 v138, v138
	v_fma_f32 v139, v139, s14, v200
	v_exp_f32_e32 v139, v139
	v_fma_f32 v140, v140, s14, v200
	v_exp_f32_e32 v140, v140
	v_fma_f32 v141, v141, s14, v200
	v_exp_f32_e32 v141, v141
	v_fma_f32 v142, v142, s14, v200
	v_exp_f32_e32 v142, v142
	v_fma_f32 v143, v143, s14, v200
	v_mfma_f32_32x32x16_bf16 v[154:169], v[10:13], v[62:65], v[154:169]
	v_exp_f32_e32 v143, v143
	v_fma_f32 v144, v144, s14, v200
	v_exp_f32_e32 v144, v144
	v_fma_f32 v145, v145, s14, v200
	v_exp_f32_e32 v145, v145
	v_fma_f32 v146, v146, s14, v200
	v_exp_f32_e32 v146, v146
	v_fma_f32 v147, v147, s14, v200
	v_exp_f32_e32 v147, v147
	v_fma_f32 v148, v148, s14, v200
	v_exp_f32_e32 v148, v148
	v_fma_f32 v149, v149, s14, v200
	v_exp_f32_e32 v149, v149
	v_fma_f32 v150, v150, s14, v200
	v_mfma_f32_32x32x16_bf16 v[154:169], v[14:17], v[66:69], v[154:169]
	v_exp_f32_e32 v150, v150
	v_fma_f32 v151, v151, s14, v200
	v_exp_f32_e32 v151, v151
	v_fma_f32 v152, v152, s14, v200
	v_exp_f32_e32 v152, v152
	v_fma_f32 v153, v153, s14, v200
	v_exp_f32_e32 v153, v153
	v_mul_f32_e32 v198, v198, v186
	v_pk_mul_f32 v[74:75], v[74:75], v[186:187] op_sel_hi:[1,0]
	v_pk_mul_f32 v[76:77], v[76:77], v[186:187] op_sel_hi:[1,0]
	v_pk_mul_f32 v[78:79], v[78:79], v[186:187] op_sel_hi:[1,0]
	v_pk_mul_f32 v[80:81], v[80:81], v[186:187] op_sel_hi:[1,0]
	v_pk_mul_f32 v[82:83], v[82:83], v[186:187] op_sel_hi:[1,0]
	v_pk_mul_f32 v[84:85], v[84:85], v[186:187] op_sel_hi:[1,0]
	v_mfma_f32_32x32x16_bf16 v[154:169], v[18:21], v[70:73], v[154:169]
	s_add_i32 s18, s16, 1
	s_lshl_b32 s17, s18, 12
	v_add_u32_e32 v207, s17, v194
	global_load_dwordx4 v[2:5], v207, s[4:5]
	global_load_dwordx4 v[6:9], v207, s[4:5] offset:1024
	global_load_dwordx4 v[10:13], v207, s[4:5] offset:2048
	global_load_dwordx4 v[14:17], v207, s[4:5] offset:3072
	s_lshl_b32 s17, s18, 9
	v_add_u32_e32 v209, s17, v190
	s_mov_b64 exec, s[44:45]
	global_load_dwordx4 v[18:21], v209, s[8:9]
	s_mov_b64 exec, -1
	v_pk_mul_f32 v[86:87], v[86:87], v[186:187] op_sel_hi:[1,0]
	v_pk_mul_f32 v[88:89], v[88:89], v[186:187] op_sel_hi:[1,0]
	v_pk_mul_f32 v[90:91], v[90:91], v[186:187] op_sel_hi:[1,0]
	v_pk_mul_f32 v[92:93], v[92:93], v[186:187] op_sel_hi:[1,0]
	v_pk_mul_f32 v[94:95], v[94:95], v[186:187] op_sel_hi:[1,0]
	v_pk_mul_f32 v[96:97], v[96:97], v[186:187] op_sel_hi:[1,0]
	v_pk_mul_f32 v[98:99], v[98:99], v[186:187] op_sel_hi:[1,0]
	v_pk_mul_f32 v[100:101], v[100:101], v[186:187] op_sel_hi:[1,0]
	v_pk_mul_f32 v[102:103], v[102:103], v[186:187] op_sel_hi:[1,0]
	v_pk_mul_f32 v[104:105], v[104:105], v[186:187] op_sel_hi:[1,0]
	v_add_f32_e32 v183, v138, v139
	v_add_f32_e32 v184, v140, v141
	v_add_f32_e32 v185, v142, v143
	v_add_f32_e32 v188, v144, v145
	v_add_f32_e32 v183, v183, v146
	v_add_f32_e32 v184, v184, v147
	v_add_f32_e32 v185, v185, v148
	v_add_f32_e32 v188, v188, v149
	v_add_f32_e32 v183, v183, v150
	v_add_f32_e32 v184, v184, v151
	v_add_f32_e32 v185, v185, v152
	v_add_f32_e32 v188, v188, v153
	v_add_f32_e32 v183, v183, v184
	v_add_f32_e32 v185, v185, v188
	v_add_f32_e32 v183, v183, v185
	v_add_f32_e32 v198, v198, v183
	v_cvt_pk_bf16_f32 v138, v138, v139
	v_cvt_pk_bf16_f32 v139, v140, v141
	v_cvt_pk_bf16_f32 v140, v142, v143
	v_cvt_pk_bf16_f32 v141, v144, v145
	v_cvt_pk_bf16_f32 v142, v146, v147
	v_cvt_pk_bf16_f32 v143, v148, v149
	v_cvt_pk_bf16_f32 v144, v150, v151
	v_cvt_pk_bf16_f32 v145, v152, v153
	v_max3_f32 v183, v154, v155, v156
	v_max3_f32 v184, v157, v158, v159
	v_max3_f32 v185, v160, v161, v162
	s_waitcnt vmcnt(5)
	v_mfma_f32_32x32x16_bf16 v[74:89], v[22:25], v[138:141], v[74:89]
	v_max3_f32 v186, v163, v164, v165
	v_max3_f32 v187, v166, v167, v168
	v_max3_f32 v183, v183, v184, v185
	v_mfma_f32_32x32x16_bf16 v[90:105], v[30:33], v[138:141], v[90:105]
	v_max3_f32 v186, v186, v187, v169
	v_max_f32_e32 v183, v183, v186
	ds_bpermute_b32 v184, v192, v183
	s_waitcnt lgkmcnt(0)
	v_max_f32_e32 v183, v183, v184
	v_fma_f32 v183, v183, s14, v203
	v_max_f32_e32 v184, v201, v183
	v_sub_f32_e32 v186, v201, v184
	v_exp_f32_e32 v186, v186
	v_mov_b32_e32 v201, v184
	v_sub_f32_e32 v204, v203, v184
	v_fma_f32 v154, v154, s14, v204
	v_exp_f32_e32 v154, v154
	v_fma_f32 v155, v155, s14, v204
	v_exp_f32_e32 v155, v155
	v_fma_f32 v156, v156, s14, v204
	v_exp_f32_e32 v156, v156
	v_fma_f32 v157, v157, s14, v204
	v_exp_f32_e32 v157, v157
	v_fma_f32 v158, v158, s14, v204
	v_exp_f32_e32 v158, v158
	v_fma_f32 v159, v159, s14, v204
	v_exp_f32_e32 v159, v159
	v_fma_f32 v160, v160, s14, v204
	v_mfma_f32_32x32x16_bf16 v[74:89], v[26:29], v[142:145], v[74:89]
	v_exp_f32_e32 v160, v160
	v_fma_f32 v161, v161, s14, v204
	v_exp_f32_e32 v161, v161
	v_fma_f32 v162, v162, s14, v204
	v_mfma_f32_32x32x16_bf16 v[90:105], v[34:37], v[142:145], v[90:105]
	v_exp_f32_e32 v162, v162
	v_fma_f32 v163, v163, s14, v204
	v_exp_f32_e32 v163, v163
	v_fma_f32 v164, v164, s14, v204
	v_exp_f32_e32 v164, v164
	v_fma_f32 v165, v165, s14, v204
	v_exp_f32_e32 v165, v165
	v_fma_f32 v166, v166, s14, v204
	v_exp_f32_e32 v166, v166
	v_fma_f32 v167, v167, s14, v204
	v_exp_f32_e32 v167, v167
	v_fma_f32 v168, v168, s14, v204
	v_exp_f32_e32 v168, v168
	v_fma_f32 v169, v169, s14, v204
	v_exp_f32_e32 v169, v169
	v_mul_f32_e32 v202, v202, v186
	v_pk_mul_f32 v[106:107], v[106:107], v[186:187] op_sel_hi:[1,0]
	v_pk_mul_f32 v[108:109], v[108:109], v[186:187] op_sel_hi:[1,0]
	v_pk_mul_f32 v[110:111], v[110:111], v[186:187] op_sel_hi:[1,0]
	v_pk_mul_f32 v[112:113], v[112:113], v[186:187] op_sel_hi:[1,0]
	v_pk_mul_f32 v[114:115], v[114:115], v[186:187] op_sel_hi:[1,0]
	v_pk_mul_f32 v[116:117], v[116:117], v[186:187] op_sel_hi:[1,0]
	v_pk_mul_f32 v[118:119], v[118:119], v[186:187] op_sel_hi:[1,0]
	v_pk_mul_f32 v[120:121], v[120:121], v[186:187] op_sel_hi:[1,0]
	v_pk_mul_f32 v[122:123], v[122:123], v[186:187] op_sel_hi:[1,0]
	v_pk_mul_f32 v[124:125], v[124:125], v[186:187] op_sel_hi:[1,0]
	v_pk_mul_f32 v[126:127], v[126:127], v[186:187] op_sel_hi:[1,0]
	v_pk_mul_f32 v[128:129], v[128:129], v[186:187] op_sel_hi:[1,0]
	v_pk_mul_f32 v[130:131], v[130:131], v[186:187] op_sel_hi:[1,0]
	v_pk_mul_f32 v[132:133], v[132:133], v[186:187] op_sel_hi:[1,0]
	v_pk_mul_f32 v[134:135], v[134:135], v[186:187] op_sel_hi:[1,0]
	v_pk_mul_f32 v[136:137], v[136:137], v[186:187] op_sel_hi:[1,0]
	v_add_f32_e32 v183, v154, v155
	v_add_f32_e32 v184, v156, v157
	v_add_f32_e32 v185, v158, v159
	v_add_f32_e32 v188, v160, v161
	v_add_f32_e32 v183, v183, v162
	v_add_f32_e32 v184, v184, v163
	v_add_f32_e32 v185, v185, v164
	v_add_f32_e32 v188, v188, v165
	v_add_f32_e32 v183, v183, v166
	v_add_f32_e32 v184, v184, v167
	v_add_f32_e32 v185, v185, v168
	v_add_f32_e32 v188, v188, v169
	v_add_f32_e32 v183, v183, v184
	v_add_f32_e32 v185, v185, v188
	v_add_f32_e32 v183, v183, v185
	v_add_f32_e32 v202, v202, v183
	v_cvt_pk_bf16_f32 v154, v154, v155
	v_cvt_pk_bf16_f32 v155, v156, v157
	v_cvt_pk_bf16_f32 v156, v158, v159
	v_cvt_pk_bf16_f32 v157, v160, v161
	v_cvt_pk_bf16_f32 v158, v162, v163
	v_cvt_pk_bf16_f32 v159, v164, v165
	v_cvt_pk_bf16_f32 v160, v166, v167
	v_cvt_pk_bf16_f32 v161, v168, v169
	s_nop 1
	v_mfma_f32_32x32x16_bf16 v[106:121], v[22:25], v[154:157], v[106:121]
	v_mfma_f32_32x32x16_bf16 v[122:137], v[30:33], v[154:157], v[122:137]
	v_mfma_f32_32x32x16_bf16 v[106:121], v[26:29], v[158:161], v[106:121]
	v_mfma_f32_32x32x16_bf16 v[122:137], v[34:37], v[158:161], v[122:137]
	s_lshl_b32 s17, s18, 12
	v_add_u32_e32 v208, s17, v194
	global_load_dwordx4 v[22:25], v208, s[6:7]
	global_load_dwordx4 v[26:29], v208, s[6:7] offset:1024
	global_load_dwordx4 v[30:33], v208, s[6:7] offset:2048
	global_load_dwordx4 v[34:37], v208, s[6:7] offset:3072
	s_add_i32 s16, s16, 1
	s_cmp_lt_u32 s16, s15
	s_cbranch_scc1 .Lfox_loop
.Lfox_tail:
	s_waitcnt vmcnt(4)
	v_mfma_f32_32x32x16_bf16 v[138:153], v[2:5], v[38:41], 0
	v_mfma_f32_32x32x16_bf16 v[138:153], v[6:9], v[42:45], v[138:153]
	v_mfma_f32_32x32x16_bf16 v[138:153], v[10:13], v[46:49], v[138:153]
	v_mfma_f32_32x32x16_bf16 v[138:153], v[14:17], v[50:53], v[138:153]
	v_mfma_f32_32x32x16_bf16 v[138:153], v[18:21], v[70:73], v[138:153]
	v_mfma_f32_32x32x16_bf16 v[154:169], v[2:5], v[54:57], 0
	s_nop 7
	s_nop 4
	v_cmp_le_i32_e64 s[34:35], 0, v170
	v_cmp_le_i32_e64 s[36:37], 1, v170
	v_cmp_le_i32_e64 s[38:39], 2, v170
	v_cmp_le_i32_e64 s[40:41], 3, v170
	v_cmp_le_i32_e32 vcc, 8, v170
	v_cndmask_b32_e64 v138, v193, v138, s[34:35]
	v_cndmask_b32_e64 v139, v193, v139, s[36:37]
	v_cndmask_b32_e64 v140, v193, v140, s[38:39]
	v_cndmask_b32_e64 v141, v193, v141, s[40:41]
	v_cndmask_b32_e64 v142, v193, v142, vcc
	v_cmp_le_i32_e64 s[34:35], 9, v170
	v_cmp_le_i32_e64 s[36:37], 10, v170
	v_cmp_le_i32_e64 s[38:39], 11, v170
	v_cmp_le_i32_e64 s[40:41], 16, v170
	v_cmp_le_i32_e32 vcc, 17, v170
	v_cndmask_b32_e64 v143, v193, v143, s[34:35]
	v_cndmask_b32_e64 v144, v193, v144, s[36:37]
	v_cndmask_b32_e64 v145, v193, v145, s[38:39]
	v_cndmask_b32_e64 v146, v193, v146, s[40:41]
	v_cndmask_b32_e64 v147, v193, v147, vcc
	v_cmp_le_i32_e64 s[34:35], 18, v170
	v_cmp_le_i32_e64 s[36:37], 19, v170
	v_cmp_le_i32_e64 s[38:39], 24, v170
	v_cmp_le_i32_e64 s[40:41], 25, v170
	v_cmp_le_i32_e32 vcc, 26, v170
	v_cndmask_b32_e64 v148, v193, v148, s[34:35]
	v_cndmask_b32_e64 v149, v193, v149, s[36:37]
	v_cndmask_b32_e64 v150, v193, v150, s[38:39]
	v_cndmask_b32_e64 v151, v193, v151, s[40:41]
	v_cndmask_b32_e64 v152, v193, v152, vcc
	v_cmp_le_i32_e64 s[34:35], 27, v170
	s_nop 1
	v_cndmask_b32_e64 v153, v193, v153, s[34:35]
	v_max3_f32 v183, v138, v139, v140
	v_max3_f32 v184, v141, v142, v143
	v_max3_f32 v185, v144, v145, v146
	v_max3_f32 v186, v147, v148, v149
	v_max3_f32 v187, v150, v151, v152
	v_max3_f32 v183, v183, v184, v185
	v_max3_f32 v186, v186, v187, v153
	v_max_f32_e32 v183, v183, v186
	ds_bpermute_b32 v184, v192, v183
	s_waitcnt lgkmcnt(0)
	v_max_f32_e32 v183, v183, v184
	v_fma_f32 v183, v183, s14, v199
	v_max_f32_e32 v184, v197, v183
	v_sub_f32_e32 v186, v197, v184
	v_mfma_f32_32x32x16_bf16 v[154:169], v[6:9], v[58:61], v[154:169]
	v_exp_f32_e32 v186, v186
	v_mov_b32_e32 v197, v184
	v_sub_f32_e32 v200, v199, v184
	v_fma_f32 v138, v138, s14, v200
	v_exp_f32_e32 v138, v138
	v_fma_f32 v139, v139, s14, v200
	v_exp_f32_e32 v139, v139
	v_fma_f32 v140, v140, s14, v200
	v_exp_f32_e32 v140, v140
	v_fma_f32 v141, v141, s14, v200
	v_exp_f32_e32 v141, v141
	v_fma_f32 v142, v142, s14, v200
	v_exp_f32_e32 v142, v142
	v_fma_f32 v143, v143, s14, v200
	v_mfma_f32_32x32x16_bf16 v[154:169], v[10:13], v[62:65], v[154:169]
	v_exp_f32_e32 v143, v143
	v_fma_f32 v144, v144, s14, v200
	v_exp_f32_e32 v144, v144
	v_fma_f32 v145, v145, s14, v200
	v_exp_f32_e32 v145, v145
	v_fma_f32 v146, v146, s14, v200
	v_exp_f32_e32 v146, v146
	v_fma_f32 v147, v147, s14, v200
	v_exp_f32_e32 v147, v147
	v_fma_f32 v148, v148, s14, v200
	v_exp_f32_e32 v148, v148
	v_fma_f32 v149, v149, s14, v200
	v_exp_f32_e32 v149, v149
	v_fma_f32 v150, v150, s14, v200
	v_mfma_f32_32x32x16_bf16 v[154:169], v[14:17], v[66:69], v[154:169]
	v_exp_f32_e32 v150, v150
	v_fma_f32 v151, v151, s14, v200
	v_exp_f32_e32 v151, v151
	v_fma_f32 v152, v152, s14, v200
	v_exp_f32_e32 v152, v152
	v_fma_f32 v153, v153, s14, v200
	v_exp_f32_e32 v153, v153
	v_mul_f32_e32 v198, v198, v186
	v_pk_mul_f32 v[74:75], v[74:75], v[186:187] op_sel_hi:[1,0]
	v_pk_mul_f32 v[76:77], v[76:77], v[186:187] op_sel_hi:[1,0]
	v_pk_mul_f32 v[78:79], v[78:79], v[186:187] op_sel_hi:[1,0]
	v_pk_mul_f32 v[80:81], v[80:81], v[186:187] op_sel_hi:[1,0]
	v_pk_mul_f32 v[82:83], v[82:83], v[186:187] op_sel_hi:[1,0]
	v_pk_mul_f32 v[84:85], v[84:85], v[186:187] op_sel_hi:[1,0]
	v_mfma_f32_32x32x16_bf16 v[154:169], v[18:21], v[70:73], v[154:169]
	s_add_i32 s18, s16, 1
	s_lshl_b32 s17, s18, 12
	v_add_u32_e32 v207, s17, v194
	global_load_dwordx4 v[2:5], v207, s[4:5]
	global_load_dwordx4 v[6:9], v207, s[4:5] offset:1024
	global_load_dwordx4 v[10:13], v207, s[4:5] offset:2048
	global_load_dwordx4 v[14:17], v207, s[4:5] offset:3072
	s_lshl_b32 s17, s18, 9
	v_add_u32_e32 v209, s17, v190
	s_mov_b64 exec, s[44:45]
	global_load_dwordx4 v[18:21], v209, s[8:9]
	s_mov_b64 exec, -1
	v_pk_mul_f32 v[86:87], v[86:87], v[186:187] op_sel_hi:[1,0]
	v_pk_mul_f32 v[88:89], v[88:89], v[186:187] op_sel_hi:[1,0]
	v_pk_mul_f32 v[90:91], v[90:91], v[186:187] op_sel_hi:[1,0]
	v_pk_mul_f32 v[92:93], v[92:93], v[186:187] op_sel_hi:[1,0]
	v_pk_mul_f32 v[94:95], v[94:95], v[186:187] op_sel_hi:[1,0]
	v_pk_mul_f32 v[96:97], v[96:97], v[186:187] op_sel_hi:[1,0]
	v_pk_mul_f32 v[98:99], v[98:99], v[186:187] op_sel_hi:[1,0]
	v_pk_mul_f32 v[100:101], v[100:101], v[186:187] op_sel_hi:[1,0]
	v_pk_mul_f32 v[102:103], v[102:103], v[186:187] op_sel_hi:[1,0]
	v_pk_mul_f32 v[104:105], v[104:105], v[186:187] op_sel_hi:[1,0]
	v_add_f32_e32 v183, v138, v139
	v_add_f32_e32 v184, v140, v141
	v_add_f32_e32 v185, v142, v143
	v_add_f32_e32 v188, v144, v145
	v_add_f32_e32 v183, v183, v146
	v_add_f32_e32 v184, v184, v147
	v_add_f32_e32 v185, v185, v148
	v_add_f32_e32 v188, v188, v149
	v_add_f32_e32 v183, v183, v150
	v_add_f32_e32 v184, v184, v151
	v_add_f32_e32 v185, v185, v152
	v_add_f32_e32 v188, v188, v153
	v_add_f32_e32 v183, v183, v184
	v_add_f32_e32 v185, v185, v188
	v_add_f32_e32 v183, v183, v185
	v_add_f32_e32 v198, v198, v183
	v_cvt_pk_bf16_f32 v138, v138, v139
	v_cvt_pk_bf16_f32 v139, v140, v141
	v_cvt_pk_bf16_f32 v140, v142, v143
	v_cvt_pk_bf16_f32 v141, v144, v145
	v_cvt_pk_bf16_f32 v142, v146, v147
	v_cvt_pk_bf16_f32 v143, v148, v149
	v_cvt_pk_bf16_f32 v144, v150, v151
	v_cvt_pk_bf16_f32 v145, v152, v153
	v_max3_f32 v183, v154, v155, v156
	v_max3_f32 v184, v157, v158, v159
	v_max3_f32 v185, v160, v161, v162
	s_waitcnt vmcnt(5)
	v_mfma_f32_32x32x16_bf16 v[74:89], v[22:25], v[138:141], v[74:89]
	v_max3_f32 v186, v163, v164, v165
	v_max3_f32 v187, v166, v167, v168
	v_max3_f32 v183, v183, v184, v185
	v_mfma_f32_32x32x16_bf16 v[90:105], v[30:33], v[138:141], v[90:105]
	v_max3_f32 v186, v186, v187, v169
	v_max_f32_e32 v183, v183, v186
	ds_bpermute_b32 v184, v192, v183
	s_waitcnt lgkmcnt(0)
	v_max_f32_e32 v183, v183, v184
	v_fma_f32 v183, v183, s14, v203
	v_max_f32_e32 v184, v201, v183
	v_sub_f32_e32 v186, v201, v184
	v_exp_f32_e32 v186, v186
	v_mov_b32_e32 v201, v184
	v_sub_f32_e32 v204, v203, v184
	v_fma_f32 v154, v154, s14, v204
	v_exp_f32_e32 v154, v154
	v_fma_f32 v155, v155, s14, v204
	v_exp_f32_e32 v155, v155
	v_fma_f32 v156, v156, s14, v204
	v_exp_f32_e32 v156, v156
	v_fma_f32 v157, v157, s14, v204
	v_exp_f32_e32 v157, v157
	v_fma_f32 v158, v158, s14, v204
	v_exp_f32_e32 v158, v158
	v_fma_f32 v159, v159, s14, v204
	v_exp_f32_e32 v159, v159
	v_fma_f32 v160, v160, s14, v204
	v_mfma_f32_32x32x16_bf16 v[74:89], v[26:29], v[142:145], v[74:89]
	v_exp_f32_e32 v160, v160
	v_fma_f32 v161, v161, s14, v204
	v_exp_f32_e32 v161, v161
	v_fma_f32 v162, v162, s14, v204
	v_mfma_f32_32x32x16_bf16 v[90:105], v[34:37], v[142:145], v[90:105]
	v_exp_f32_e32 v162, v162
	v_fma_f32 v163, v163, s14, v204
	v_exp_f32_e32 v163, v163
	v_fma_f32 v164, v164, s14, v204
	v_exp_f32_e32 v164, v164
	v_fma_f32 v165, v165, s14, v204
	v_exp_f32_e32 v165, v165
	v_fma_f32 v166, v166, s14, v204
	v_exp_f32_e32 v166, v166
	v_fma_f32 v167, v167, s14, v204
	v_exp_f32_e32 v167, v167
	v_fma_f32 v168, v168, s14, v204
	v_exp_f32_e32 v168, v168
	v_fma_f32 v169, v169, s14, v204
	v_exp_f32_e32 v169, v169
	v_mul_f32_e32 v202, v202, v186
	v_pk_mul_f32 v[106:107], v[106:107], v[186:187] op_sel_hi:[1,0]
	v_pk_mul_f32 v[108:109], v[108:109], v[186:187] op_sel_hi:[1,0]
	v_pk_mul_f32 v[110:111], v[110:111], v[186:187] op_sel_hi:[1,0]
	v_pk_mul_f32 v[112:113], v[112:113], v[186:187] op_sel_hi:[1,0]
	v_pk_mul_f32 v[114:115], v[114:115], v[186:187] op_sel_hi:[1,0]
	v_pk_mul_f32 v[116:117], v[116:117], v[186:187] op_sel_hi:[1,0]
	v_pk_mul_f32 v[118:119], v[118:119], v[186:187] op_sel_hi:[1,0]
	v_pk_mul_f32 v[120:121], v[120:121], v[186:187] op_sel_hi:[1,0]
	v_pk_mul_f32 v[122:123], v[122:123], v[186:187] op_sel_hi:[1,0]
	v_pk_mul_f32 v[124:125], v[124:125], v[186:187] op_sel_hi:[1,0]
	v_pk_mul_f32 v[126:127], v[126:127], v[186:187] op_sel_hi:[1,0]
	v_pk_mul_f32 v[128:129], v[128:129], v[186:187] op_sel_hi:[1,0]
	v_pk_mul_f32 v[130:131], v[130:131], v[186:187] op_sel_hi:[1,0]
	v_pk_mul_f32 v[132:133], v[132:133], v[186:187] op_sel_hi:[1,0]
	v_pk_mul_f32 v[134:135], v[134:135], v[186:187] op_sel_hi:[1,0]
	v_pk_mul_f32 v[136:137], v[136:137], v[186:187] op_sel_hi:[1,0]
	v_add_f32_e32 v183, v154, v155
	v_add_f32_e32 v184, v156, v157
	v_add_f32_e32 v185, v158, v159
	v_add_f32_e32 v188, v160, v161
	v_add_f32_e32 v183, v183, v162
	v_add_f32_e32 v184, v184, v163
	v_add_f32_e32 v185, v185, v164
	v_add_f32_e32 v188, v188, v165
	v_add_f32_e32 v183, v183, v166
	v_add_f32_e32 v184, v184, v167
	v_add_f32_e32 v185, v185, v168
	v_add_f32_e32 v188, v188, v169
	v_add_f32_e32 v183, v183, v184
	v_add_f32_e32 v185, v185, v188
	v_add_f32_e32 v183, v183, v185
	v_add_f32_e32 v202, v202, v183
	v_cvt_pk_bf16_f32 v154, v154, v155
	v_cvt_pk_bf16_f32 v155, v156, v157
	v_cvt_pk_bf16_f32 v156, v158, v159
	v_cvt_pk_bf16_f32 v157, v160, v161
	v_cvt_pk_bf16_f32 v158, v162, v163
	v_cvt_pk_bf16_f32 v159, v164, v165
	v_cvt_pk_bf16_f32 v160, v166, v167
	v_cvt_pk_bf16_f32 v161, v168, v169
	s_nop 1
	v_mfma_f32_32x32x16_bf16 v[106:121], v[22:25], v[154:157], v[106:121]
	v_mfma_f32_32x32x16_bf16 v[122:137], v[30:33], v[154:157], v[122:137]
	v_mfma_f32_32x32x16_bf16 v[106:121], v[26:29], v[158:161], v[106:121]
	v_mfma_f32_32x32x16_bf16 v[122:137], v[34:37], v[158:161], v[122:137]
	s_lshl_b32 s17, s18, 12
	v_add_u32_e32 v208, s17, v194
	global_load_dwordx4 v[22:25], v208, s[6:7]
	global_load_dwordx4 v[26:29], v208, s[6:7] offset:1024
	global_load_dwordx4 v[30:33], v208, s[6:7] offset:2048
	global_load_dwordx4 v[34:37], v208, s[6:7] offset:3072
	s_add_i32 s16, s16, 1
	s_waitcnt vmcnt(4)
	v_mfma_f32_32x32x16_bf16 v[154:169], v[2:5], v[54:57], 0
	v_mfma_f32_32x32x16_bf16 v[154:169], v[6:9], v[58:61], v[154:169]
	v_mfma_f32_32x32x16_bf16 v[154:169], v[10:13], v[62:65], v[154:169]
	v_mfma_f32_32x32x16_bf16 v[154:169], v[14:17], v[66:69], v[154:169]
	v_mfma_f32_32x32x16_bf16 v[154:169], v[18:21], v[70:73], v[154:169]
	s_nop 7
	s_nop 4
	v_cmp_le_i32_e64 s[34:35], 0, v170
	v_cmp_le_i32_e64 s[36:37], 1, v170
	v_cmp_le_i32_e64 s[38:39], 2, v170
	v_cmp_le_i32_e64 s[40:41], 3, v170
	v_cmp_le_i32_e32 vcc, 8, v170
	v_cndmask_b32_e64 v154, v193, v154, s[34:35]
	v_cndmask_b32_e64 v155, v193, v155, s[36:37]
	v_cndmask_b32_e64 v156, v193, v156, s[38:39]
	v_cndmask_b32_e64 v157, v193, v157, s[40:41]
	v_cndmask_b32_e64 v158, v193, v158, vcc
	v_cmp_le_i32_e64 s[34:35], 9, v170
	v_cmp_le_i32_e64 s[36:37], 10, v170
	v_cmp_le_i32_e64 s[38:39], 11, v170
	v_cmp_le_i32_e64 s[40:41], 16, v170
	v_cmp_le_i32_e32 vcc, 17, v170
	v_cndmask_b32_e64 v159, v193, v159, s[34:35]
	v_cndmask_b32_e64 v160, v193, v160, s[36:37]
	v_cndmask_b32_e64 v161, v193, v161, s[38:39]
	v_cndmask_b32_e64 v162, v193, v162, s[40:41]
	v_cndmask_b32_e64 v163, v193, v163, vcc
	v_cmp_le_i32_e64 s[34:35], 18, v170
	v_cmp_le_i32_e64 s[36:37], 19, v170
	v_cmp_le_i32_e64 s[38:39], 24, v170
	v_cmp_le_i32_e64 s[40:41], 25, v170
	v_cmp_le_i32_e32 vcc, 26, v170
	v_cndmask_b32_e64 v164, v193, v164, s[34:35]
	v_cndmask_b32_e64 v165, v193, v165, s[36:37]
	v_cndmask_b32_e64 v166, v193, v166, s[38:39]
	v_cndmask_b32_e64 v167, v193, v167, s[40:41]
	v_cndmask_b32_e64 v168, v193, v168, vcc
	v_cmp_le_i32_e64 s[34:35], 27, v170
	s_nop 1
	v_cndmask_b32_e64 v169, v193, v169, s[34:35]
	v_max3_f32 v183, v154, v155, v156
	v_max3_f32 v184, v157, v158, v159
	v_max3_f32 v185, v160, v161, v162
	v_max3_f32 v186, v163, v164, v165
	v_max3_f32 v187, v166, v167, v168
	v_max3_f32 v183, v183, v184, v185
	v_max3_f32 v186, v186, v187, v169
	v_max_f32_e32 v183, v183, v186
	ds_bpermute_b32 v184, v192, v183
	s_waitcnt lgkmcnt(0)
	s_waitcnt vmcnt(0)
	v_max_f32_e32 v183, v183, v184
	v_fma_f32 v183, v183, s14, v203
	v_max_f32_e32 v184, v201, v183
	v_sub_f32_e32 v186, v201, v184
	v_exp_f32_e32 v186, v186
	v_mov_b32_e32 v201, v184
	v_sub_f32_e32 v204, v203, v184
	v_fma_f32 v154, v154, s14, v204
	v_exp_f32_e32 v154, v154
	v_fma_f32 v155, v155, s14, v204
	v_exp_f32_e32 v155, v155
	v_fma_f32 v156, v156, s14, v204
	v_exp_f32_e32 v156, v156
	v_fma_f32 v157, v157, s14, v204
	v_exp_f32_e32 v157, v157
	v_fma_f32 v158, v158, s14, v204
	v_exp_f32_e32 v158, v158
	v_fma_f32 v159, v159, s14, v204
	v_exp_f32_e32 v159, v159
	v_fma_f32 v160, v160, s14, v204
	v_exp_f32_e32 v160, v160
	v_fma_f32 v161, v161, s14, v204
	v_exp_f32_e32 v161, v161
	v_fma_f32 v162, v162, s14, v204
	v_exp_f32_e32 v162, v162
	v_fma_f32 v163, v163, s14, v204
	v_exp_f32_e32 v163, v163
	v_fma_f32 v164, v164, s14, v204
	v_exp_f32_e32 v164, v164
	v_fma_f32 v165, v165, s14, v204
	v_exp_f32_e32 v165, v165
	v_fma_f32 v166, v166, s14, v204
	v_exp_f32_e32 v166, v166
	v_fma_f32 v167, v167, s14, v204
	v_exp_f32_e32 v167, v167
	v_fma_f32 v168, v168, s14, v204
	v_exp_f32_e32 v168, v168
	v_fma_f32 v169, v169, s14, v204
	v_exp_f32_e32 v169, v169
	v_mul_f32_e32 v202, v202, v186
	v_pk_mul_f32 v[106:107], v[106:107], v[186:187] op_sel_hi:[1,0]
	v_pk_mul_f32 v[108:109], v[108:109], v[186:187] op_sel_hi:[1,0]
	v_pk_mul_f32 v[110:111], v[110:111], v[186:187] op_sel_hi:[1,0]
	v_pk_mul_f32 v[112:113], v[112:113], v[186:187] op_sel_hi:[1,0]
	v_pk_mul_f32 v[114:115], v[114:115], v[186:187] op_sel_hi:[1,0]
	v_pk_mul_f32 v[116:117], v[116:117], v[186:187] op_sel_hi:[1,0]
	v_pk_mul_f32 v[118:119], v[118:119], v[186:187] op_sel_hi:[1,0]
	v_pk_mul_f32 v[120:121], v[120:121], v[186:187] op_sel_hi:[1,0]
	v_pk_mul_f32 v[122:123], v[122:123], v[186:187] op_sel_hi:[1,0]
	v_pk_mul_f32 v[124:125], v[124:125], v[186:187] op_sel_hi:[1,0]
	v_pk_mul_f32 v[126:127], v[126:127], v[186:187] op_sel_hi:[1,0]
	v_pk_mul_f32 v[128:129], v[128:129], v[186:187] op_sel_hi:[1,0]
	v_pk_mul_f32 v[130:131], v[130:131], v[186:187] op_sel_hi:[1,0]
	v_pk_mul_f32 v[132:133], v[132:133], v[186:187] op_sel_hi:[1,0]
	v_pk_mul_f32 v[134:135], v[134:135], v[186:187] op_sel_hi:[1,0]
	v_pk_mul_f32 v[136:137], v[136:137], v[186:187] op_sel_hi:[1,0]
	v_add_f32_e32 v183, v154, v155
	v_add_f32_e32 v184, v156, v157
	v_add_f32_e32 v185, v158, v159
	v_add_f32_e32 v188, v160, v161
	v_add_f32_e32 v183, v183, v162
	v_add_f32_e32 v184, v184, v163
	v_add_f32_e32 v185, v185, v164
	v_add_f32_e32 v188, v188, v165
	v_add_f32_e32 v183, v183, v166
	v_add_f32_e32 v184, v184, v167
	v_add_f32_e32 v185, v185, v168
	v_add_f32_e32 v188, v188, v169
	v_add_f32_e32 v183, v183, v184
	v_add_f32_e32 v185, v185, v188
	v_add_f32_e32 v183, v183, v185
	v_add_f32_e32 v202, v202, v183
	v_cvt_pk_bf16_f32 v154, v154, v155
	v_cvt_pk_bf16_f32 v155, v156, v157
	v_cvt_pk_bf16_f32 v156, v158, v159
	v_cvt_pk_bf16_f32 v157, v160, v161
	v_cvt_pk_bf16_f32 v158, v162, v163
	v_cvt_pk_bf16_f32 v159, v164, v165
	v_cvt_pk_bf16_f32 v160, v166, v167
	v_cvt_pk_bf16_f32 v161, v168, v169
	s_nop 1
	v_mfma_f32_32x32x16_bf16 v[106:121], v[22:25], v[154:157], v[106:121]
	v_mfma_f32_32x32x16_bf16 v[122:137], v[30:33], v[154:157], v[122:137]
	v_mfma_f32_32x32x16_bf16 v[106:121], v[26:29], v[158:161], v[106:121]
	v_mfma_f32_32x32x16_bf16 v[122:137], v[34:37], v[158:161], v[122:137]
	s_nop 7
	s_nop 7
	ds_bpermute_b32 v184, v192, v198
	s_waitcnt lgkmcnt(0)
	v_add_f32_e32 v198, v198, v184
	v_rcp_f32_e32 v186, v198
	s_nop 0
	v_fma_f32 v184, -v198, v186, 1.0
	v_fma_f32 v186, v186, v184, v186
	v_pk_mul_f32 v[74:75], v[74:75], v[186:187] op_sel_hi:[1,0]
	v_pk_mul_f32 v[76:77], v[76:77], v[186:187] op_sel_hi:[1,0]
	v_pk_mul_f32 v[78:79], v[78:79], v[186:187] op_sel_hi:[1,0]
	v_pk_mul_f32 v[80:81], v[80:81], v[186:187] op_sel_hi:[1,0]
	v_pk_mul_f32 v[82:83], v[82:83], v[186:187] op_sel_hi:[1,0]
	v_pk_mul_f32 v[84:85], v[84:85], v[186:187] op_sel_hi:[1,0]
	v_pk_mul_f32 v[86:87], v[86:87], v[186:187] op_sel_hi:[1,0]
	v_pk_mul_f32 v[88:89], v[88:89], v[186:187] op_sel_hi:[1,0]
	v_pk_mul_f32 v[90:91], v[90:91], v[186:187] op_sel_hi:[1,0]
	v_pk_mul_f32 v[92:93], v[92:93], v[186:187] op_sel_hi:[1,0]
	v_pk_mul_f32 v[94:95], v[94:95], v[186:187] op_sel_hi:[1,0]
	v_pk_mul_f32 v[96:97], v[96:97], v[186:187] op_sel_hi:[1,0]
	v_pk_mul_f32 v[98:99], v[98:99], v[186:187] op_sel_hi:[1,0]
	v_pk_mul_f32 v[100:101], v[100:101], v[186:187] op_sel_hi:[1,0]
	v_pk_mul_f32 v[102:103], v[102:103], v[186:187] op_sel_hi:[1,0]
	v_pk_mul_f32 v[104:105], v[104:105], v[186:187] op_sel_hi:[1,0]
	v_cvt_pk_bf16_f32 v74, v74, v75
	v_cvt_pk_bf16_f32 v75, v76, v77
	global_store_dwordx2 v205, v[74:75], s[12:13]
	v_cvt_pk_bf16_f32 v78, v78, v79
	v_cvt_pk_bf16_f32 v79, v80, v81
	global_store_dwordx2 v205, v[78:79], s[12:13] offset:16
	v_cvt_pk_bf16_f32 v82, v82, v83
	v_cvt_pk_bf16_f32 v83, v84, v85
	global_store_dwordx2 v205, v[82:83], s[12:13] offset:32
	v_cvt_pk_bf16_f32 v86, v86, v87
	v_cvt_pk_bf16_f32 v87, v88, v89
	global_store_dwordx2 v205, v[86:87], s[12:13] offset:48
	v_cvt_pk_bf16_f32 v90, v90, v91
	v_cvt_pk_bf16_f32 v91, v92, v93
	global_store_dwordx2 v205, v[90:91], s[12:13] offset:64
	v_cvt_pk_bf16_f32 v94, v94, v95
	v_cvt_pk_bf16_f32 v95, v96, v97
	global_store_dwordx2 v205, v[94:95], s[12:13] offset:80
	v_cvt_pk_bf16_f32 v98, v98, v99
	v_cvt_pk_bf16_f32 v99, v100, v101
	global_store_dwordx2 v205, v[98:99], s[12:13] offset:96
	v_cvt_pk_bf16_f32 v102, v102, v103
	v_cvt_pk_bf16_f32 v103, v104, v105
	global_store_dwordx2 v205, v[102:103], s[12:13] offset:112
	ds_bpermute_b32 v184, v192, v202
	s_waitcnt lgkmcnt(0)
	v_add_f32_e32 v202, v202, v184
	v_rcp_f32_e32 v186, v202
	s_nop 0
	v_fma_f32 v184, -v202, v186, 1.0
	v_fma_f32 v186, v186, v184, v186
	v_pk_mul_f32 v[106:107], v[106:107], v[186:187] op_sel_hi:[1,0]
	v_pk_mul_f32 v[108:109], v[108:109], v[186:187] op_sel_hi:[1,0]
	v_pk_mul_f32 v[110:111], v[110:111], v[186:187] op_sel_hi:[1,0]
	v_pk_mul_f32 v[112:113], v[112:113], v[186:187] op_sel_hi:[1,0]
	v_pk_mul_f32 v[114:115], v[114:115], v[186:187] op_sel_hi:[1,0]
	v_pk_mul_f32 v[116:117], v[116:117], v[186:187] op_sel_hi:[1,0]
	v_pk_mul_f32 v[118:119], v[118:119], v[186:187] op_sel_hi:[1,0]
	v_pk_mul_f32 v[120:121], v[120:121], v[186:187] op_sel_hi:[1,0]
	v_pk_mul_f32 v[122:123], v[122:123], v[186:187] op_sel_hi:[1,0]
	v_pk_mul_f32 v[124:125], v[124:125], v[186:187] op_sel_hi:[1,0]
	v_pk_mul_f32 v[126:127], v[126:127], v[186:187] op_sel_hi:[1,0]
	v_pk_mul_f32 v[128:129], v[128:129], v[186:187] op_sel_hi:[1,0]
	v_pk_mul_f32 v[130:131], v[130:131], v[186:187] op_sel_hi:[1,0]
	v_pk_mul_f32 v[132:133], v[132:133], v[186:187] op_sel_hi:[1,0]
	v_pk_mul_f32 v[134:135], v[134:135], v[186:187] op_sel_hi:[1,0]
	v_pk_mul_f32 v[136:137], v[136:137], v[186:187] op_sel_hi:[1,0]
	v_cvt_pk_bf16_f32 v106, v106, v107
	v_cvt_pk_bf16_f32 v107, v108, v109
	global_store_dwordx2 v206, v[106:107], s[12:13]
	v_cvt_pk_bf16_f32 v110, v110, v111
	v_cvt_pk_bf16_f32 v111, v112, v113
	global_store_dwordx2 v206, v[110:111], s[12:13] offset:16
	v_cvt_pk_bf16_f32 v114, v114, v115
	v_cvt_pk_bf16_f32 v115, v116, v117
	global_store_dwordx2 v206, v[114:115], s[12:13] offset:32
	v_cvt_pk_bf16_f32 v118, v118, v119
	v_cvt_pk_bf16_f32 v119, v120, v121
	global_store_dwordx2 v206, v[118:119], s[12:13] offset:48
	v_cvt_pk_bf16_f32 v122, v122, v123
	v_cvt_pk_bf16_f32 v123, v124, v125
	global_store_dwordx2 v206, v[122:123], s[12:13] offset:64
	v_cvt_pk_bf16_f32 v126, v126, v127
	v_cvt_pk_bf16_f32 v127, v128, v129
	global_store_dwordx2 v206, v[126:127], s[12:13] offset:80
	v_cvt_pk_bf16_f32 v130, v130, v131
	v_cvt_pk_bf16_f32 v131, v132, v133
	global_store_dwordx2 v206, v[130:131], s[12:13] offset:96
	v_cvt_pk_bf16_f32 v134, v134, v135
	v_cvt_pk_bf16_f32 v135, v136, v137
	global_store_dwordx2 v206, v[134:135], s[12:13] offset:112
	s_waitcnt vmcnt(0)
	s_add_i32 s22, s22, s68
	s_cmpk_lt_i32 s22, 0x800
	s_cbranch_scc1 .Lfox_outer
	v_lshlrev_b32_e32 v2, 2, v220
	v_add_u32_e32 v3, 0x10000, v2
	ds_read_b32 v146, v2 offset:0
	ds_read_b32 v147, v2 offset:2048
	ds_read_b32 v148, v2 offset:4096
	ds_read_b32 v149, v2 offset:6144
	ds_read_b32 v150, v2 offset:8192
	ds_read_b32 v151, v2 offset:10240
	ds_read_b32 v152, v2 offset:12288
	ds_read_b32 v153, v2 offset:14336
	ds_read_b32 v154, v2 offset:16384
	ds_read_b32 v155, v2 offset:18432
	ds_read_b32 v156, v2 offset:20480
	ds_read_b32 v157, v2 offset:22528
	ds_read_b32 v158, v2 offset:24576
	ds_read_b32 v159, v2 offset:26624
	ds_read_b32 v160, v2 offset:28672
	ds_read_b32 v161, v2 offset:30720
	ds_read_b32 v162, v2 offset:32768
	ds_read_b32 v163, v2 offset:34816
	ds_read_b32 v164, v2 offset:36864
	ds_read_b32 v165, v2 offset:38912
	ds_read_b32 v166, v2 offset:40960
	ds_read_b32 v167, v2 offset:43008
	ds_read_b32 v168, v2 offset:45056
	ds_read_b32 v169, v2 offset:47104
	ds_read_b32 v170, v2 offset:49152
	ds_read_b32 v183, v2 offset:51200
	ds_read_b32 v184, v2 offset:53248
	ds_read_b32 v185, v2 offset:55296
	ds_read_b32 v186, v2 offset:57344
	ds_read_b32 v187, v2 offset:59392
	ds_read_b32 v188, v2 offset:61440
	ds_read_b32 v189, v2 offset:63488
	ds_read_b32 v190, v3 offset:0
	ds_read_b32 v191, v3 offset:2048
	ds_read_b32 v192, v3 offset:4096
	ds_read_b32 v193, v3 offset:6144
	ds_read_b32 v194, v3 offset:8192
	ds_read_b32 v195, v3 offset:10240
	ds_read_b32 v196, v3 offset:12288
	ds_read_b32 v197, v3 offset:14336
	ds_read_b32 v198, v3 offset:16384
	ds_read_b32 v199, v3 offset:18432
	ds_read_b32 v200, v3 offset:20480
	ds_read_b32 v201, v3 offset:22528
	ds_read_b32 v202, v3 offset:24576
	ds_read_b32 v203, v3 offset:26624
	ds_read_b32 v204, v3 offset:28672
	ds_read_b32 v205, v3 offset:30720
	ds_read_b32 v206, v3 offset:32768
	ds_read_b32 v207, v3 offset:34816
	ds_read_b32 v208, v3 offset:36864
	ds_read_b32 v209, v3 offset:38912
	ds_read_b32 v210, v3 offset:40960
	ds_read_b32 v211, v3 offset:43008
	ds_read_b32 v212, v3 offset:45056
	ds_read_b32 v213, v3 offset:47104
	ds_read_b32 v214, v3 offset:49152
	ds_read_b32 v215, v3 offset:51200
	ds_read_b32 v216, v3 offset:53248
	v_lshrrev_b32_e32 v2, 6, v220
	v_lshlrev_b32_e32 v2, 8, v2
	v_add_u32_e32 v2, 0x1d800, v2
	ds_read_b32 v4, v2 offset:0
	ds_read_b32 v5, v2 offset:4
	ds_read_b32 v6, v2 offset:8
	ds_read_b32 v7, v2 offset:12
	ds_read_b32 v8, v2 offset:16
	ds_read_b32 v9, v2 offset:20
	ds_read_b32 v10, v2 offset:24
	ds_read_b32 v11, v2 offset:28
	ds_read_b32 v12, v2 offset:32
	ds_read_b32 v13, v2 offset:36
	ds_read_b32 v14, v2 offset:40
	ds_read_b32 v15, v2 offset:44
	ds_read_b32 v16, v2 offset:48
	ds_read_b32 v17, v2 offset:52
	ds_read_b32 v18, v2 offset:56
	ds_read_b32 v19, v2 offset:60
	ds_read_b32 v20, v2 offset:64
	ds_read_b32 v21, v2 offset:68
	ds_read_b32 v22, v2 offset:72
	ds_read_b32 v23, v2 offset:76
	ds_read_b32 v24, v2 offset:80
	ds_read_b32 v25, v2 offset:84
	ds_read_b32 v26, v2 offset:88
	ds_read_b32 v27, v2 offset:92
	ds_read_b32 v28, v2 offset:96
	ds_read_b32 v29, v2 offset:100
	ds_read_b32 v30, v2 offset:104
	ds_read_b32 v31, v2 offset:108
	ds_read_b32 v32, v2 offset:112
	ds_read_b32 v33, v2 offset:116
	ds_read_b32 v34, v2 offset:120
	ds_read_b32 v35, v2 offset:124
	ds_read_b32 v36, v2 offset:128
	ds_read_b32 v37, v2 offset:132
	ds_read_b32 v38, v2 offset:136
	ds_read_b32 v39, v2 offset:140
	ds_read_b32 v40, v2 offset:144
	ds_read_b32 v41, v2 offset:148
	ds_read_b32 v42, v2 offset:152
	ds_read_b32 v43, v2 offset:156
	ds_read_b32 v44, v2 offset:160
	ds_read_b32 v45, v2 offset:164
	s_waitcnt lgkmcnt(0)
	v_readfirstlane_b32 s2, v4
	v_readfirstlane_b32 s3, v5
	v_readfirstlane_b32 s4, v6
	v_readfirstlane_b32 s5, v7
	v_readfirstlane_b32 s6, v8
	v_readfirstlane_b32 s7, v9
	v_readfirstlane_b32 s8, v10
	v_readfirstlane_b32 s9, v11
	v_readfirstlane_b32 s10, v12
	v_readfirstlane_b32 s11, v13
	v_readfirstlane_b32 s12, v14
	v_readfirstlane_b32 s13, v15
	v_readfirstlane_b32 s14, v16
	v_readfirstlane_b32 s15, v17
	v_readfirstlane_b32 s16, v18
	v_readfirstlane_b32 s17, v19
	v_readfirstlane_b32 s18, v20
	v_readfirstlane_b32 s19, v21
	v_readfirstlane_b32 s20, v22
	v_readfirstlane_b32 s21, v23
	v_readfirstlane_b32 s22, v24
	v_readfirstlane_b32 s23, v25
	v_readfirstlane_b32 s24, v26
	v_readfirstlane_b32 s25, v27
	v_readfirstlane_b32 s26, v28
	v_readfirstlane_b32 s27, v29
	v_readfirstlane_b32 s28, v30
	v_readfirstlane_b32 s29, v31
	v_readfirstlane_b32 s30, v32
	v_readfirstlane_b32 s31, v33
	v_readfirstlane_b32 s34, v34
	v_readfirstlane_b32 s35, v35
	v_readfirstlane_b32 s36, v36
	v_readfirstlane_b32 s37, v37
	v_readfirstlane_b32 s38, v38
	v_readfirstlane_b32 s39, v39
	v_readfirstlane_b32 s40, v40
	v_readfirstlane_b32 s41, v41
	v_readfirstlane_b32 s42, v42
	v_readfirstlane_b32 s43, v43
	v_readfirstlane_b32 s44, v44
	v_readfirstlane_b32 s45, v45
.Lfox_exit:
	s_barrier
	s_branch .LBB0_715
